# S1: R9 + split-K partial-sum loads in sample_rows_norm issued as one batch (same add order) instead of load/wait chain
# speedup vs baseline: 1.0042x; 1.0042x over previous
.LBB0_808:
	s_add_i32 s8, s52, 0x2000
	s_and_b64 s[26:27], s[4:5], exec
	s_cselect_b32 s26, s52, s8
	s_ashr_i32 s27, s26, 31
	s_lshl_b64 s[26:27], s[26:27], 13
	v_lshl_add_u64 v[2:3], v[16:17], 0, s[26:27]
	global_load_dwordx4 v[2:5], v[2:3], off
	v_readlane_b32 s0, v253, 47
	v_readlane_b32 s1, v253, 48
	s_andn2_b64 vcc, exec, s[0:1]
	s_cbranch_vccnz .LBB0_812
	s_mov_b32 s40, 0x46800000
	s_mov_b32 s41, 0
	v_lshl_add_u64 v[100:101], v[18:19], 0, s[40:41]
	global_load_dwordx4 v[100:103], v[100:101], off
	s_add_u32 s40, s40, 0x100000
	v_lshl_add_u64 v[104:105], v[18:19], 0, s[40:41]
	global_load_dwordx4 v[104:107], v[104:105], off
	s_add_u32 s40, s40, 0x100000
	v_lshl_add_u64 v[108:109], v[18:19], 0, s[40:41]
	global_load_dwordx4 v[108:111], v[108:109], off
	s_add_u32 s40, s40, 0x100000
	v_lshl_add_u64 v[112:113], v[18:19], 0, s[40:41]
	global_load_dwordx4 v[112:115], v[112:113], off
	s_add_u32 s40, s40, 0x100000
	v_lshl_add_u64 v[116:117], v[18:19], 0, s[40:41]
	global_load_dwordx4 v[116:119], v[116:117], off
	s_add_u32 s40, s40, 0x100000
	v_lshl_add_u64 v[120:121], v[18:19], 0, s[40:41]
	global_load_dwordx4 v[120:123], v[120:121], off
	s_add_u32 s40, s40, 0x100000
	v_lshl_add_u64 v[124:125], v[18:19], 0, s[40:41]
	global_load_dwordx4 v[124:127], v[124:125], off
	s_add_u32 s40, s40, 0x100000
	v_lshl_add_u64 v[128:129], v[18:19], 0, s[40:41]
	global_load_dwordx4 v[128:131], v[128:129], off
	s_add_u32 s40, s40, 0x100000
	v_lshl_add_u64 v[132:133], v[18:19], 0, s[40:41]
	global_load_dwordx4 v[132:135], v[132:133], off
	s_add_u32 s40, s40, 0x100000
	v_lshl_add_u64 v[136:137], v[18:19], 0, s[40:41]
	global_load_dwordx4 v[136:139], v[136:137], off
	s_add_u32 s40, s40, 0x100000
	v_lshl_add_u64 v[154:155], v[18:19], 0, s[40:41]
	global_load_dwordx4 v[154:157], v[154:155], off
	s_add_u32 s40, s40, 0x100000
	v_lshl_add_u64 v[166:167], v[18:19], 0, s[40:41]
	global_load_dwordx4 v[166:169], v[166:167], off
	s_add_u32 s40, s40, 0x100000
	v_lshl_add_u64 v[170:171], v[18:19], 0, s[40:41]
	global_load_dwordx4 v[170:173], v[170:171], off
	s_add_u32 s40, s40, 0x100000
	v_lshl_add_u64 v[174:175], v[18:19], 0, s[40:41]
	global_load_dwordx4 v[174:177], v[174:175], off
	s_add_u32 s40, s40, 0x100000
	v_lshl_add_u64 v[178:179], v[18:19], 0, s[40:41]
	global_load_dwordx4 v[178:181], v[178:179], off
	s_add_u32 s40, s40, 0x100000
	v_lshl_add_u64 v[182:183], v[18:19], 0, s[40:41]
	global_load_dwordx4 v[182:185], v[182:183], off
	s_add_u32 s40, s40, 0x100000
	v_lshl_add_u64 v[186:187], v[18:19], 0, s[40:41]
	global_load_dwordx4 v[186:189], v[186:187], off
	s_add_u32 s40, s40, 0x100000
	v_lshl_add_u64 v[190:191], v[18:19], 0, s[40:41]
	global_load_dwordx4 v[190:193], v[190:191], off
	s_add_u32 s40, s40, 0x100000
	v_lshl_add_u64 v[204:205], v[18:19], 0, s[40:41]
	global_load_dwordx4 v[204:207], v[204:205], off
	s_add_u32 s40, s40, 0x100000
	v_lshl_add_u64 v[208:209], v[18:19], 0, s[40:41]
	global_load_dwordx4 v[208:211], v[208:209], off
	s_add_u32 s40, s40, 0x100000
	v_lshl_add_u64 v[212:213], v[18:19], 0, s[40:41]
	global_load_dwordx4 v[212:215], v[212:213], off
	s_add_i32 s0, s52, 4
	v_mad_i64_i32 v[32:33], s[26:27], s0, v237, v[10:11]
	global_load_dwordx4 v[32:35], v[32:33], off
	v_mov_b32_e32 v20, 0
	v_mov_b32_e32 v21, 0
	v_mov_b32_e32 v22, 0
	v_mov_b32_e32 v23, 0
	s_waitcnt vmcnt(21)
	v_pk_add_f32 v[20:21], v[20:21], v[100:101]
	v_pk_add_f32 v[22:23], v[22:23], v[102:103]
	s_waitcnt vmcnt(20)
	v_pk_add_f32 v[20:21], v[20:21], v[104:105]
	v_pk_add_f32 v[22:23], v[22:23], v[106:107]
	s_waitcnt vmcnt(19)
	v_pk_add_f32 v[20:21], v[20:21], v[108:109]
	v_pk_add_f32 v[22:23], v[22:23], v[110:111]
	s_waitcnt vmcnt(18)
	v_pk_add_f32 v[20:21], v[20:21], v[112:113]
	v_pk_add_f32 v[22:23], v[22:23], v[114:115]
	s_waitcnt vmcnt(17)
	v_pk_add_f32 v[20:21], v[20:21], v[116:117]
	v_pk_add_f32 v[22:23], v[22:23], v[118:119]
	s_waitcnt vmcnt(16)
	v_pk_add_f32 v[20:21], v[20:21], v[120:121]
	v_pk_add_f32 v[22:23], v[22:23], v[122:123]
	s_waitcnt vmcnt(15)
	v_pk_add_f32 v[20:21], v[20:21], v[124:125]
	v_pk_add_f32 v[22:23], v[22:23], v[126:127]
	s_waitcnt vmcnt(14)
	v_pk_add_f32 v[20:21], v[20:21], v[128:129]
	v_pk_add_f32 v[22:23], v[22:23], v[130:131]
	s_waitcnt vmcnt(13)
	v_pk_add_f32 v[20:21], v[20:21], v[132:133]
	v_pk_add_f32 v[22:23], v[22:23], v[134:135]
	s_waitcnt vmcnt(12)
	v_pk_add_f32 v[20:21], v[20:21], v[136:137]
	v_pk_add_f32 v[22:23], v[22:23], v[138:139]
	s_waitcnt vmcnt(11)
	v_pk_add_f32 v[20:21], v[20:21], v[154:155]
	v_pk_add_f32 v[22:23], v[22:23], v[156:157]
	s_waitcnt vmcnt(10)
	v_pk_add_f32 v[20:21], v[20:21], v[166:167]
	v_pk_add_f32 v[22:23], v[22:23], v[168:169]
	s_waitcnt vmcnt(9)
	v_pk_add_f32 v[20:21], v[20:21], v[170:171]
	v_pk_add_f32 v[22:23], v[22:23], v[172:173]
	s_waitcnt vmcnt(8)
	v_pk_add_f32 v[20:21], v[20:21], v[174:175]
	v_pk_add_f32 v[22:23], v[22:23], v[176:177]
	s_waitcnt vmcnt(7)
	v_pk_add_f32 v[20:21], v[20:21], v[178:179]
	v_pk_add_f32 v[22:23], v[22:23], v[180:181]
	s_waitcnt vmcnt(6)
	v_pk_add_f32 v[20:21], v[20:21], v[182:183]
	v_pk_add_f32 v[22:23], v[22:23], v[184:185]
	s_waitcnt vmcnt(5)
	v_pk_add_f32 v[20:21], v[20:21], v[186:187]
	v_pk_add_f32 v[22:23], v[22:23], v[188:189]
	s_waitcnt vmcnt(4)
	v_pk_add_f32 v[20:21], v[20:21], v[190:191]
	v_pk_add_f32 v[22:23], v[22:23], v[192:193]
	s_waitcnt vmcnt(3)
	v_pk_add_f32 v[20:21], v[20:21], v[204:205]
	v_pk_add_f32 v[22:23], v[22:23], v[206:207]
	s_waitcnt vmcnt(2)
	v_pk_add_f32 v[20:21], v[20:21], v[208:209]
	v_pk_add_f32 v[22:23], v[22:23], v[210:211]
	s_waitcnt vmcnt(1)
	v_pk_add_f32 v[20:21], v[20:21], v[212:213]
	v_pk_add_f32 v[22:23], v[22:23], v[214:215]
	s_waitcnt vmcnt(0)
	v_pk_mul_f32 v[34:35], v[34:35], 0.5 op_sel_hi:[1,0]
	v_pk_mul_f32 v[32:33], v[32:33], 0.5 op_sel_hi:[1,0]
	v_pk_fma_f32 v[4:5], v[22:23], v[34:35], v[4:5]
	v_pk_fma_f32 v[2:3], v[20:21], v[32:33], v[2:3]

.LBB0_1055:
	s_add_i32 s8, s46, 0x2000
	s_ashr_i32 s9, s8, 31
	s_lshl_b64 s[26:27], s[8:9], 13
	v_lshl_add_u64 v[18:19], v[8:9], 0, s[26:27]
	global_load_dwordx4 v[2:5], v[18:19], off
	s_mov_b32 s44, 0x46800000
	s_mov_b32 s45, 0
	v_lshl_add_u64 v[100:101], v[16:17], 0, s[44:45]
	global_load_dwordx4 v[100:103], v[100:101], off
	s_add_u32 s44, s44, 0x100000
	v_lshl_add_u64 v[104:105], v[16:17], 0, s[44:45]
	global_load_dwordx4 v[104:107], v[104:105], off
	s_add_u32 s44, s44, 0x100000
	v_lshl_add_u64 v[108:109], v[16:17], 0, s[44:45]
	global_load_dwordx4 v[108:111], v[108:109], off
	s_add_u32 s44, s44, 0x100000
	v_lshl_add_u64 v[112:113], v[16:17], 0, s[44:45]
	global_load_dwordx4 v[112:115], v[112:113], off
	s_add_u32 s44, s44, 0x100000
	v_lshl_add_u64 v[116:117], v[16:17], 0, s[44:45]
	global_load_dwordx4 v[116:119], v[116:117], off
	s_add_u32 s44, s44, 0x100000
	v_lshl_add_u64 v[120:121], v[16:17], 0, s[44:45]
	global_load_dwordx4 v[120:123], v[120:121], off
	s_add_u32 s44, s44, 0x100000
	v_lshl_add_u64 v[124:125], v[16:17], 0, s[44:45]
	global_load_dwordx4 v[124:127], v[124:125], off
	s_add_u32 s44, s44, 0x100000
	v_lshl_add_u64 v[128:129], v[16:17], 0, s[44:45]
	global_load_dwordx4 v[128:131], v[128:129], off
	s_add_u32 s44, s44, 0x100000
	v_lshl_add_u64 v[132:133], v[16:17], 0, s[44:45]
	global_load_dwordx4 v[132:135], v[132:133], off
	s_add_u32 s44, s44, 0x100000
	v_lshl_add_u64 v[136:137], v[16:17], 0, s[44:45]
	global_load_dwordx4 v[136:139], v[136:137], off
	s_add_u32 s44, s44, 0x100000
	v_lshl_add_u64 v[154:155], v[16:17], 0, s[44:45]
	global_load_dwordx4 v[154:157], v[154:155], off
	s_add_u32 s44, s44, 0x100000
	v_lshl_add_u64 v[166:167], v[16:17], 0, s[44:45]
	global_load_dwordx4 v[166:169], v[166:167], off
	s_add_u32 s44, s44, 0x100000
	v_lshl_add_u64 v[170:171], v[16:17], 0, s[44:45]
	global_load_dwordx4 v[170:173], v[170:171], off
	s_add_u32 s44, s44, 0x100000
	v_lshl_add_u64 v[174:175], v[16:17], 0, s[44:45]
	global_load_dwordx4 v[174:177], v[174:175], off
	s_add_u32 s44, s44, 0x100000
	v_lshl_add_u64 v[178:179], v[16:17], 0, s[44:45]
	global_load_dwordx4 v[178:181], v[178:179], off
	s_add_u32 s44, s44, 0x100000
	v_lshl_add_u64 v[182:183], v[16:17], 0, s[44:45]
	global_load_dwordx4 v[182:185], v[182:183], off
	s_add_u32 s44, s44, 0x100000
	v_lshl_add_u64 v[186:187], v[16:17], 0, s[44:45]
	global_load_dwordx4 v[186:189], v[186:187], off
	s_add_u32 s44, s44, 0x100000
	v_lshl_add_u64 v[190:191], v[16:17], 0, s[44:45]
	global_load_dwordx4 v[190:193], v[190:191], off
	s_add_u32 s44, s44, 0x100000
	v_lshl_add_u64 v[204:205], v[16:17], 0, s[44:45]
	global_load_dwordx4 v[204:207], v[204:205], off
	s_add_u32 s44, s44, 0x100000
	v_lshl_add_u64 v[208:209], v[16:17], 0, s[44:45]
	global_load_dwordx4 v[208:211], v[208:209], off
	s_add_u32 s44, s44, 0x100000
	v_lshl_add_u64 v[212:213], v[16:17], 0, s[44:45]
	global_load_dwordx4 v[212:215], v[212:213], off
	s_add_i32 s27, s46, 4
	v_mad_i64_i32 v[32:33], s[28:29], s27, v237, v[10:11]
	global_load_dwordx4 v[32:35], v[32:33], off
	v_mov_b32_e32 v20, 0
	v_mov_b32_e32 v21, 0
	v_mov_b32_e32 v22, 0
	v_mov_b32_e32 v23, 0
	s_waitcnt vmcnt(21)
	v_pk_add_f32 v[20:21], v[20:21], v[100:101]
	v_pk_add_f32 v[22:23], v[22:23], v[102:103]
	s_waitcnt vmcnt(20)
	v_pk_add_f32 v[20:21], v[20:21], v[104:105]
	v_pk_add_f32 v[22:23], v[22:23], v[106:107]
	s_waitcnt vmcnt(19)
	v_pk_add_f32 v[20:21], v[20:21], v[108:109]
	v_pk_add_f32 v[22:23], v[22:23], v[110:111]
	s_waitcnt vmcnt(18)
	v_pk_add_f32 v[20:21], v[20:21], v[112:113]
	v_pk_add_f32 v[22:23], v[22:23], v[114:115]
	s_waitcnt vmcnt(17)
	v_pk_add_f32 v[20:21], v[20:21], v[116:117]
	v_pk_add_f32 v[22:23], v[22:23], v[118:119]
	s_waitcnt vmcnt(16)
	v_pk_add_f32 v[20:21], v[20:21], v[120:121]
	v_pk_add_f32 v[22:23], v[22:23], v[122:123]
	s_waitcnt vmcnt(15)
	v_pk_add_f32 v[20:21], v[20:21], v[124:125]
	v_pk_add_f32 v[22:23], v[22:23], v[126:127]
	s_waitcnt vmcnt(14)
	v_pk_add_f32 v[20:21], v[20:21], v[128:129]
	v_pk_add_f32 v[22:23], v[22:23], v[130:131]
	s_waitcnt vmcnt(13)
	v_pk_add_f32 v[20:21], v[20:21], v[132:133]
	v_pk_add_f32 v[22:23], v[22:23], v[134:135]
	s_waitcnt vmcnt(12)
	v_pk_add_f32 v[20:21], v[20:21], v[136:137]
	v_pk_add_f32 v[22:23], v[22:23], v[138:139]
	s_waitcnt vmcnt(11)
	v_pk_add_f32 v[20:21], v[20:21], v[154:155]
	v_pk_add_f32 v[22:23], v[22:23], v[156:157]
	s_waitcnt vmcnt(10)
	v_pk_add_f32 v[20:21], v[20:21], v[166:167]
	v_pk_add_f32 v[22:23], v[22:23], v[168:169]
	s_waitcnt vmcnt(9)
	v_pk_add_f32 v[20:21], v[20:21], v[170:171]
	v_pk_add_f32 v[22:23], v[22:23], v[172:173]
	s_waitcnt vmcnt(8)
	v_pk_add_f32 v[20:21], v[20:21], v[174:175]
	v_pk_add_f32 v[22:23], v[22:23], v[176:177]
	s_waitcnt vmcnt(7)
	v_pk_add_f32 v[20:21], v[20:21], v[178:179]
	v_pk_add_f32 v[22:23], v[22:23], v[180:181]
	s_waitcnt vmcnt(6)
	v_pk_add_f32 v[20:21], v[20:21], v[182:183]
	v_pk_add_f32 v[22:23], v[22:23], v[184:185]
	s_waitcnt vmcnt(5)
	v_pk_add_f32 v[20:21], v[20:21], v[186:187]
	v_pk_add_f32 v[22:23], v[22:23], v[188:189]
	s_waitcnt vmcnt(4)
	v_pk_add_f32 v[20:21], v[20:21], v[190:191]
	v_pk_add_f32 v[22:23], v[22:23], v[192:193]
	s_waitcnt vmcnt(3)
	v_pk_add_f32 v[20:21], v[20:21], v[204:205]
	v_pk_add_f32 v[22:23], v[22:23], v[206:207]
	s_waitcnt vmcnt(2)
	v_pk_add_f32 v[20:21], v[20:21], v[208:209]
	v_pk_add_f32 v[22:23], v[22:23], v[210:211]
	s_waitcnt vmcnt(1)
	v_pk_add_f32 v[20:21], v[20:21], v[212:213]
	v_pk_add_f32 v[22:23], v[22:23], v[214:215]
	s_waitcnt vmcnt(0)
	v_pk_mul_f32 v[34:35], v[34:35], 0.5 op_sel_hi:[1,0]
	v_pk_mul_f32 v[32:33], v[32:33], 0.5 op_sel_hi:[1,0]
	v_pk_fma_f32 v[4:5], v[22:23], v[34:35], v[4:5]
	v_pk_fma_f32 v[2:3], v[20:21], v[32:33], v[2:3]
	v_mul_f32_e32 v21, v5, v5
	v_mul_f32_e32 v20, v3, v3
	v_fmac_f32_e32 v20, v2, v2
	v_fmac_f32_e32 v21, v4, v4
	v_add_f32_e32 v20, v20, v21
	ds_bpermute_b32 v21, v25, v20
	global_store_dwordx4 v[18:19], v[2:5], off
	s_waitcnt lgkmcnt(0)
	v_add_f32_e32 v20, v20, v21
	ds_bpermute_b32 v21, v26, v20
	s_waitcnt lgkmcnt(0)
	v_add_f32_e32 v20, v20, v21
	ds_bpermute_b32 v21, v27, v20
	s_waitcnt lgkmcnt(0)
	v_add_f32_e32 v20, v20, v21
	ds_bpermute_b32 v21, v28, v20
	s_waitcnt lgkmcnt(0)
	v_add_f32_e32 v20, v20, v21
	ds_bpermute_b32 v21, v29, v20
	s_waitcnt lgkmcnt(0)
	v_add_f32_e32 v20, v20, v21
	ds_bpermute_b32 v21, v30, v20
	s_and_saveexec_b64 s[44:45], s[42:43]
	s_cbranch_execz .LBB0_1054
	s_waitcnt lgkmcnt(0)
	v_add_f32_e32 v18, v20, v21
	v_mov_b32_e32 v19, s11
	ds_write_b32 v19, v18
	s_branch .LBB0_1054

.LBB0_2425:
	s_add_i32 s8, s46, 0x2000
	s_ashr_i32 s9, s8, 31
	s_lshl_b64 s[0:1], s[8:9], 13
	v_lshl_add_u64 v[18:19], v[8:9], 0, s[0:1]
	global_load_dwordx4 v[2:5], v[18:19], off
	s_mov_b32 s44, 0x46800000
	s_mov_b32 s45, 0
	v_lshl_add_u64 v[100:101], v[16:17], 0, s[44:45]
	global_load_dwordx4 v[100:103], v[100:101], off
	s_add_u32 s44, s44, 0x100000
	v_lshl_add_u64 v[104:105], v[16:17], 0, s[44:45]
	global_load_dwordx4 v[104:107], v[104:105], off
	s_add_u32 s44, s44, 0x100000
	v_lshl_add_u64 v[108:109], v[16:17], 0, s[44:45]
	global_load_dwordx4 v[108:111], v[108:109], off
	s_add_u32 s44, s44, 0x100000
	v_lshl_add_u64 v[112:113], v[16:17], 0, s[44:45]
	global_load_dwordx4 v[112:115], v[112:113], off
	s_add_u32 s44, s44, 0x100000
	v_lshl_add_u64 v[116:117], v[16:17], 0, s[44:45]
	global_load_dwordx4 v[116:119], v[116:117], off
	s_add_u32 s44, s44, 0x100000
	v_lshl_add_u64 v[120:121], v[16:17], 0, s[44:45]
	global_load_dwordx4 v[120:123], v[120:121], off
	s_add_u32 s44, s44, 0x100000
	v_lshl_add_u64 v[124:125], v[16:17], 0, s[44:45]
	global_load_dwordx4 v[124:127], v[124:125], off
	s_add_u32 s44, s44, 0x100000
	v_lshl_add_u64 v[128:129], v[16:17], 0, s[44:45]
	global_load_dwordx4 v[128:131], v[128:129], off
	s_add_i32 s27, s46, 4
	v_mad_i64_i32 v[24:25], s[0:1], s27, v237, v[10:11]
	global_load_dwordx4 v[24:27], v[24:25], off
	s_mov_b64 s[48:49], -1
	v_mov_b32_e32 v20, 0
	v_mov_b32_e32 v21, 0
	v_mov_b32_e32 v22, 0
	v_mov_b32_e32 v23, 0
	s_waitcnt vmcnt(8)
	v_pk_add_f32 v[20:21], v[20:21], v[100:101]
	v_pk_add_f32 v[22:23], v[22:23], v[102:103]
	s_waitcnt vmcnt(7)
	v_pk_add_f32 v[20:21], v[20:21], v[104:105]
	v_pk_add_f32 v[22:23], v[22:23], v[106:107]
	s_waitcnt vmcnt(6)
	v_pk_add_f32 v[20:21], v[20:21], v[108:109]
	v_pk_add_f32 v[22:23], v[22:23], v[110:111]
	s_waitcnt vmcnt(5)
	v_pk_add_f32 v[20:21], v[20:21], v[112:113]
	v_pk_add_f32 v[22:23], v[22:23], v[114:115]
	s_waitcnt vmcnt(4)
	v_pk_add_f32 v[20:21], v[20:21], v[116:117]
	v_pk_add_f32 v[22:23], v[22:23], v[118:119]
	s_waitcnt vmcnt(3)
	v_pk_add_f32 v[20:21], v[20:21], v[120:121]
	v_pk_add_f32 v[22:23], v[22:23], v[122:123]
	s_waitcnt vmcnt(2)
	v_pk_add_f32 v[20:21], v[20:21], v[124:125]
	v_pk_add_f32 v[22:23], v[22:23], v[126:127]
	s_waitcnt vmcnt(1)
	v_pk_add_f32 v[20:21], v[20:21], v[128:129]
	v_pk_add_f32 v[22:23], v[22:23], v[130:131]
	s_waitcnt vmcnt(0)
	v_pk_fma_f32 v[4:5], v[22:23], v[26:27], v[4:5]
	v_pk_fma_f32 v[2:3], v[20:21], v[24:25], v[2:3]
	v_mul_f32_e32 v21, v5, v5
	v_mul_f32_e32 v20, v3, v3
	v_fmac_f32_e32 v20, v2, v2
	v_fmac_f32_e32 v21, v4, v4
	v_add_f32_e32 v20, v20, v21
	ds_bpermute_b32 v21, v31, v20
	global_store_dwordx4 v[18:19], v[2:5], off
	s_waitcnt lgkmcnt(0)
	v_add_f32_e32 v20, v20, v21
	ds_bpermute_b32 v21, v32, v20
	s_waitcnt lgkmcnt(0)
	v_add_f32_e32 v20, v20, v21
	ds_bpermute_b32 v21, v33, v20
	s_waitcnt lgkmcnt(0)
	v_add_f32_e32 v20, v20, v21
	ds_bpermute_b32 v21, v34, v20
	s_waitcnt lgkmcnt(0)
	v_add_f32_e32 v20, v20, v21
	ds_bpermute_b32 v21, v35, v20
	s_waitcnt lgkmcnt(0)
	v_add_f32_e32 v20, v20, v21
	ds_bpermute_b32 v21, v36, v20
	s_and_saveexec_b64 s[44:45], s[42:43]
	s_cbranch_execz .LBB0_2424
	s_waitcnt lgkmcnt(0)
	v_add_f32_e32 v18, v20, v21
	v_mov_b32_e32 v19, s11
	ds_write_b32 v19, v18
	s_branch .LBB0_2424

.LBB0_2651:
	s_ashr_i32 s93, s92, 31
	s_lshl_b64 s[2:3], s[92:93], 13
	s_add_u32 s2, s2, 0x4000000
	s_addc_u32 s3, s3, 0
	v_lshl_add_u64 v[0:1], v[4:5], 0, s[2:3]
	global_load_dwordx4 v[0:3], v[0:1], off
	s_mov_b32 s12, 0x46800000
	s_mov_b32 s13, 0
	v_lshl_add_u64 v[100:101], v[12:13], 0, s[12:13]
	global_load_dwordx4 v[100:103], v[100:101], off
	s_add_u32 s12, s12, 0x100000
	v_lshl_add_u64 v[104:105], v[12:13], 0, s[12:13]
	global_load_dwordx4 v[104:107], v[104:105], off
	s_add_u32 s12, s12, 0x100000
	v_lshl_add_u64 v[108:109], v[12:13], 0, s[12:13]
	global_load_dwordx4 v[108:111], v[108:109], off
	s_add_u32 s12, s12, 0x100000
	v_lshl_add_u64 v[112:113], v[12:13], 0, s[12:13]
	global_load_dwordx4 v[112:115], v[112:113], off
	s_add_u32 s12, s12, 0x100000
	v_lshl_add_u64 v[116:117], v[12:13], 0, s[12:13]
	global_load_dwordx4 v[116:119], v[116:117], off
	s_add_u32 s12, s12, 0x100000
	v_lshl_add_u64 v[120:121], v[12:13], 0, s[12:13]
	global_load_dwordx4 v[120:123], v[120:121], off
	s_add_u32 s12, s12, 0x100000
	v_lshl_add_u64 v[124:125], v[12:13], 0, s[12:13]
	global_load_dwordx4 v[124:127], v[124:125], off
	s_add_u32 s12, s12, 0x100000
	v_lshl_add_u64 v[128:129], v[12:13], 0, s[12:13]
	global_load_dwordx4 v[128:131], v[128:129], off
	s_add_u32 s12, s12, 0x100000
	v_lshl_add_u64 v[132:133], v[12:13], 0, s[12:13]
	global_load_dwordx4 v[132:135], v[132:133], off
	s_add_u32 s12, s12, 0x100000
	v_lshl_add_u64 v[136:137], v[12:13], 0, s[12:13]
	global_load_dwordx4 v[136:139], v[136:137], off
	s_add_u32 s12, s12, 0x100000
	v_lshl_add_u64 v[154:155], v[12:13], 0, s[12:13]
	global_load_dwordx4 v[154:157], v[154:155], off
	s_add_u32 s12, s12, 0x100000
	v_lshl_add_u64 v[166:167], v[12:13], 0, s[12:13]
	global_load_dwordx4 v[166:169], v[166:167], off
	s_add_u32 s12, s12, 0x100000
	v_lshl_add_u64 v[170:171], v[12:13], 0, s[12:13]
	global_load_dwordx4 v[170:173], v[170:171], off
	s_add_u32 s12, s12, 0x100000
	v_lshl_add_u64 v[174:175], v[12:13], 0, s[12:13]
	global_load_dwordx4 v[174:177], v[174:175], off
	s_add_u32 s12, s12, 0x100000
	v_lshl_add_u64 v[178:179], v[12:13], 0, s[12:13]
	global_load_dwordx4 v[178:181], v[178:179], off
	s_add_u32 s12, s12, 0x100000
	v_lshl_add_u64 v[182:183], v[12:13], 0, s[12:13]
	global_load_dwordx4 v[182:185], v[182:183], off
	s_add_u32 s12, s12, 0x100000
	v_lshl_add_u64 v[186:187], v[12:13], 0, s[12:13]
	global_load_dwordx4 v[186:189], v[186:187], off
	s_add_u32 s12, s12, 0x100000
	v_lshl_add_u64 v[190:191], v[12:13], 0, s[12:13]
	global_load_dwordx4 v[190:193], v[190:191], off
	s_add_u32 s12, s12, 0x100000
	v_lshl_add_u64 v[204:205], v[12:13], 0, s[12:13]
	global_load_dwordx4 v[204:207], v[204:205], off
	s_add_u32 s12, s12, 0x100000
	v_lshl_add_u64 v[208:209], v[12:13], 0, s[12:13]
	global_load_dwordx4 v[208:211], v[208:209], off
	s_add_u32 s12, s12, 0x100000
	v_lshl_add_u64 v[212:213], v[12:13], 0, s[12:13]
	global_load_dwordx4 v[212:215], v[212:213], off
	s_add_i32 s12, s92, 4
	v_mad_i64_i32 v[28:29], s[12:13], s12, v26, v[6:7]
	global_load_dwordx4 v[28:31], v[28:29], off
	v_mov_b32_e32 v14, 0
	v_mov_b32_e32 v15, 0
	v_mov_b32_e32 v16, 0
	v_mov_b32_e32 v17, 0
	s_waitcnt vmcnt(21)
	v_pk_add_f32 v[14:15], v[14:15], v[100:101]
	v_pk_add_f32 v[16:17], v[16:17], v[102:103]
	s_waitcnt vmcnt(20)
	v_pk_add_f32 v[14:15], v[14:15], v[104:105]
	v_pk_add_f32 v[16:17], v[16:17], v[106:107]
	s_waitcnt vmcnt(19)
	v_pk_add_f32 v[14:15], v[14:15], v[108:109]
	v_pk_add_f32 v[16:17], v[16:17], v[110:111]
	s_waitcnt vmcnt(18)
	v_pk_add_f32 v[14:15], v[14:15], v[112:113]
	v_pk_add_f32 v[16:17], v[16:17], v[114:115]
	s_waitcnt vmcnt(17)
	v_pk_add_f32 v[14:15], v[14:15], v[116:117]
	v_pk_add_f32 v[16:17], v[16:17], v[118:119]
	s_waitcnt vmcnt(16)
	v_pk_add_f32 v[14:15], v[14:15], v[120:121]
	v_pk_add_f32 v[16:17], v[16:17], v[122:123]
	s_waitcnt vmcnt(15)
	v_pk_add_f32 v[14:15], v[14:15], v[124:125]
	v_pk_add_f32 v[16:17], v[16:17], v[126:127]
	s_waitcnt vmcnt(14)
	v_pk_add_f32 v[14:15], v[14:15], v[128:129]
	v_pk_add_f32 v[16:17], v[16:17], v[130:131]
	s_waitcnt vmcnt(13)
	v_pk_add_f32 v[14:15], v[14:15], v[132:133]
	v_pk_add_f32 v[16:17], v[16:17], v[134:135]
	s_waitcnt vmcnt(12)
	v_pk_add_f32 v[14:15], v[14:15], v[136:137]
	v_pk_add_f32 v[16:17], v[16:17], v[138:139]
	s_waitcnt vmcnt(11)
	v_pk_add_f32 v[14:15], v[14:15], v[154:155]
	v_pk_add_f32 v[16:17], v[16:17], v[156:157]
	s_waitcnt vmcnt(10)
	v_pk_add_f32 v[14:15], v[14:15], v[166:167]
	v_pk_add_f32 v[16:17], v[16:17], v[168:169]
	s_waitcnt vmcnt(9)
	v_pk_add_f32 v[14:15], v[14:15], v[170:171]
	v_pk_add_f32 v[16:17], v[16:17], v[172:173]
	s_waitcnt vmcnt(8)
	v_pk_add_f32 v[14:15], v[14:15], v[174:175]
	v_pk_add_f32 v[16:17], v[16:17], v[176:177]
	s_waitcnt vmcnt(7)
	v_pk_add_f32 v[14:15], v[14:15], v[178:179]
	v_pk_add_f32 v[16:17], v[16:17], v[180:181]
	s_waitcnt vmcnt(6)
	v_pk_add_f32 v[14:15], v[14:15], v[182:183]
	v_pk_add_f32 v[16:17], v[16:17], v[184:185]
	s_waitcnt vmcnt(5)
	v_pk_add_f32 v[14:15], v[14:15], v[186:187]
	v_pk_add_f32 v[16:17], v[16:17], v[188:189]
	s_waitcnt vmcnt(4)
	v_pk_add_f32 v[14:15], v[14:15], v[190:191]
	v_pk_add_f32 v[16:17], v[16:17], v[192:193]
	s_waitcnt vmcnt(3)
	v_pk_add_f32 v[14:15], v[14:15], v[204:205]
	v_pk_add_f32 v[16:17], v[16:17], v[206:207]
	s_waitcnt vmcnt(2)
	v_pk_add_f32 v[14:15], v[14:15], v[208:209]
	v_pk_add_f32 v[16:17], v[16:17], v[210:211]
	s_waitcnt vmcnt(1)
	v_pk_add_f32 v[14:15], v[14:15], v[212:213]
	v_pk_add_f32 v[16:17], v[16:17], v[214:215]
	s_waitcnt vmcnt(0)
	v_pk_mul_f32 v[30:31], v[30:31], 0.5 op_sel_hi:[1,0]
	v_pk_mul_f32 v[28:29], v[28:29], 0.5 op_sel_hi:[1,0]
	v_pk_fma_f32 v[2:3], v[16:17], v[30:31], v[2:3]
	v_pk_fma_f32 v[0:1], v[14:15], v[28:29], v[0:1]
	v_mul_f32_e32 v15, v3, v3
	v_mul_f32_e32 v14, v1, v1
	v_fmac_f32_e32 v14, v0, v0
	v_fmac_f32_e32 v15, v2, v2
	v_add_f32_e32 v14, v14, v15
	ds_bpermute_b32 v15, v18, v14
	s_waitcnt lgkmcnt(0)
	v_add_f32_e32 v14, v14, v15
	ds_bpermute_b32 v15, v19, v14
	s_waitcnt lgkmcnt(0)
	v_add_f32_e32 v14, v14, v15
	ds_bpermute_b32 v15, v20, v14
	s_waitcnt lgkmcnt(0)
	v_add_f32_e32 v14, v14, v15
	ds_bpermute_b32 v15, v21, v14
	s_waitcnt lgkmcnt(0)
	v_add_f32_e32 v14, v14, v15
	ds_bpermute_b32 v15, v22, v14
	s_waitcnt lgkmcnt(0)
	v_add_f32_e32 v14, v14, v15
	ds_bpermute_b32 v15, v23, v14
	s_and_saveexec_b64 s[12:13], s[0:1]
	s_cbranch_execz .LBB0_2650
	s_waitcnt lgkmcnt(0)
	v_add_f32_e32 v14, v14, v15
	v_mov_b32_e32 v15, s15
	ds_write_b32 v15, v14
	s_branch .LBB0_2650
